# final rmsnorm loop rewritten: norm weights loaded once, 4 row sums per chunk in one load, no per-float4 drains
# speedup vs baseline: 1.0908x; 1.0064x over previous
; __global__ void __launch_bounds__(512, 2) mega(Params P0) {
;     ...
;         else if (ph == 11) { const float* r3 = (const float*)(ws + WS_RSS3); const float* fw = P.in[23]; const f32x4* h3 = (const f32x4*)(ws + WS_H1);
;             const int nchunk = NTOK * DM / 4 / 1024; const int wv = bid * 8 + (tid >> 6), lane = tid & 63;
;             for (int ck = wv; ck < nchunk; ck += G * 8) { f32x4 v[16];
; #pragma unroll
;                 for (int j = 0; j < 16; ++j) v[j] = __builtin_nontemporal_load(h3 + (ck * 16 + j) * 64 + lane);
; #pragma unroll
;                 for (int j = 0; j < 16; ++j) { const int i = (ck * 16 + j) * 64 + lane; const int row = i >> 8, c4 = i & 255; const float rstd = rsqrtf(r3[row] * (1.0f / DM) + 1e-6f);
;                     __builtin_nontemporal_store(v[j] * rstd * *(const f32x4*)(fw + 4 * c4), (f32x4*)P.out + i); } } }
.LBB0_719:
	s_and_b64 vcc, exec, s[90:91]
	v_readlane_b32 s26, v255, 24
	s_cbranch_vccz .LBB0_1023
	s_add_i32 s84, s80, -6
	s_cmp_gt_u32 s84, 3
	s_mov_b64 s[2:3], -1
	s_movk_i32 s28, 0x5000
	s_mov_b32 s54, 0x3e6d3388
	s_cbranch_scc0 .LBB0_801
	s_cmp_lt_i32 s80, 11
	s_cbranch_scc1 .LBB0_728
	s_cmp_eq_u32 s80, 11
	s_cbranch_scc0 .LBB0_727
	v_ashrrev_i32_e32 v2, 6, v186
	v_lshl_add_u32 v100, s77, 3, v2
	v_cmp_gt_i32_e32 vcc, s83, v100
	s_and_saveexec_b64 s[2:3], vcc
	v_readlane_b32 s40, v255, 2
	v_readlane_b32 s54, v255, 16
	v_readlane_b32 s55, v255, 17
	v_readlane_b32 s41, v255, 3
	v_readlane_b32 s42, v255, 4
	v_readlane_b32 s43, v255, 5
	v_readlane_b32 s44, v255, 6
	v_readlane_b32 s45, v255, 7
	v_readlane_b32 s46, v255, 8
	v_readlane_b32 s47, v255, 9
	v_readlane_b32 s48, v255, 10
	v_readlane_b32 s49, v255, 11
	v_readlane_b32 s50, v255, 12
	v_readlane_b32 s51, v255, 13
	v_readlane_b32 s52, v255, 14
	v_readlane_b32 s53, v255, 15
	s_cbranch_execz .LBB0_726
	s_add_u32 s4, s22, 0xd320000
	s_addc_u32 s5, s23, 0
	v_and_b32_e32 v0, 63, v186
	s_waitcnt lgkmcnt(0)
	v_lshlrev_b32_e32 v3, 12, v2
	s_lshl_b32 s6, s77, 13
	v_lshlrev_b32_e32 v4, 4, v0
	v_mov_b32_e32 v5, v1
	v_readlane_b32 s7, v255, 18
	v_lshl_add_u32 v3, s77, 15, v3
	v_lshl_add_u32 v2, v2, 10, s6
	s_waitcnt vmcnt(0)
	v_lshl_add_u64 v[66:67], s[22:23], 0, v[4:5]
	s_lshl_b32 s0, s7, 3
	v_lshl_add_u64 v[68:69], s[54:55], 0, v[4:5]
	v_lshl_or_b32 v101, v0, 2, v3
	s_lshl_b32 s8, s7, 15
	v_or_b32_e32 v70, 0x3c0, v2
	s_lshl_b32 s9, s7, 13
	s_mov_b64 s[6:7], 0
	global_load_dwordx4 v[108:111], v[68:69], off
	global_load_dwordx4 v[112:115], v[68:69], off offset:1024
	global_load_dwordx4 v[116:119], v[68:69], off offset:2048
	global_load_dwordx4 v[120:123], v[68:69], off offset:3072
	s_waitcnt vmcnt(0)
.LBB0_725:
	v_add_u32_e32 v102, 0xfffffc40, v70
	v_ashrrev_i32_e32 v103, 31, v102
	v_ashrrev_i32_e32 v104, 8, v102
	v_ashrrev_i32_e32 v105, 31, v104
	v_lshl_add_u64 v[104:105], v[104:105], 2, s[4:5]
	global_load_dwordx4 v[76:79], v[104:105], off
	v_lshl_add_u64 v[88:89], v[102:103], 4, v[66:67]
	global_load_dwordx4 v[62:65], v[88:89], off nt
	global_load_dwordx4 v[58:61], v[88:89], off offset:1024 nt
	global_load_dwordx4 v[54:57], v[88:89], off offset:2048 nt
	global_load_dwordx4 v[50:53], v[88:89], off offset:3072 nt
	v_add_u32_e32 v90, 0x100, v102
	v_ashrrev_i32_e32 v91, 31, v90
	v_lshl_add_u64 v[90:91], v[90:91], 4, v[66:67]
	global_load_dwordx4 v[46:49], v[90:91], off nt
	global_load_dwordx4 v[42:45], v[90:91], off offset:1024 nt
	global_load_dwordx4 v[38:41], v[90:91], off offset:2048 nt
	global_load_dwordx4 v[34:37], v[90:91], off offset:3072 nt
	v_add_u32_e32 v92, 0x200, v102
	v_ashrrev_i32_e32 v93, 31, v92
	v_lshl_add_u64 v[92:93], v[92:93], 4, v[66:67]
	global_load_dwordx4 v[30:33], v[92:93], off nt
	global_load_dwordx4 v[26:29], v[92:93], off offset:1024 nt
	global_load_dwordx4 v[22:25], v[92:93], off offset:2048 nt
	global_load_dwordx4 v[18:21], v[92:93], off offset:3072 nt
	v_add_u32_e32 v94, 0x300, v102
	v_ashrrev_i32_e32 v95, 31, v94
	v_lshl_add_u64 v[94:95], v[94:95], 4, v[66:67]
	global_load_dwordx4 v[14:17], v[94:95], off nt
	global_load_dwordx4 v[10:13], v[94:95], off offset:1024 nt
	global_load_dwordx4 v[6:9], v[94:95], off offset:2048 nt
	global_load_dwordx4 v[2:5], v[94:95], off offset:3072 nt
	v_add_u32_e32 v100, s0, v100
	s_movk_i32 s10, 0x1fff
	v_add_u32_e32 v72, v0, v102
	v_ashrrev_i32_e32 v73, 31, v72
	v_lshl_add_u64 v[72:73], v[72:73], 4, s[20:21]
	v_add_u32_e32 v74, v0, v102
	v_add_u32_e32 v74, 0x100, v74
	v_ashrrev_i32_e32 v75, 31, v74
	v_lshl_add_u64 v[74:75], v[74:75], 4, s[20:21]
	v_add_u32_e32 v96, v0, v102
	v_add_u32_e32 v96, 0x200, v96
	v_ashrrev_i32_e32 v97, 31, v96
	v_lshl_add_u64 v[96:97], v[96:97], 4, s[20:21]
	v_add_u32_e32 v98, v0, v102
	v_add_u32_e32 v98, 0x300, v98
	v_ashrrev_i32_e32 v99, 31, v98
	v_lshl_add_u64 v[98:99], v[98:99], 4, s[20:21]
	s_waitcnt vmcnt(16)
	v_fmamk_f32 v80, v76, 0x3a800000, v210
	v_fmamk_f32 v82, v77, 0x3a800000, v210
	v_fmamk_f32 v84, v78, 0x3a800000, v210
	v_fmamk_f32 v86, v79, 0x3a800000, v210
	v_cmp_gt_f32_e64 s[40:41], s30, v80
	v_mul_f32_e32 v81, 0x4b800000, v80
	v_cmp_gt_f32_e64 s[42:43], s30, v82
	v_mul_f32_e32 v83, 0x4b800000, v82
	v_cmp_gt_f32_e64 s[44:45], s30, v84
	v_mul_f32_e32 v85, 0x4b800000, v84
	v_cmp_gt_f32_e64 s[46:47], s30, v86
	v_mul_f32_e32 v87, 0x4b800000, v86
	v_cndmask_b32_e64 v80, v80, v81, s[40:41]
	v_cndmask_b32_e64 v82, v82, v83, s[42:43]
	v_cndmask_b32_e64 v84, v84, v85, s[44:45]
	v_cndmask_b32_e64 v86, v86, v87, s[46:47]
	v_rsq_f32_e32 v80, v80
	v_rsq_f32_e32 v82, v82
	v_rsq_f32_e32 v84, v84
	v_rsq_f32_e32 v86, v86
	v_mul_f32_e32 v81, 0x45800000, v80
	v_mul_f32_e32 v83, 0x45800000, v82
	v_mul_f32_e32 v85, 0x45800000, v84
	v_mul_f32_e32 v87, 0x45800000, v86
	v_cndmask_b32_e64 v80, v80, v81, s[40:41]
	v_cndmask_b32_e64 v82, v82, v83, s[42:43]
	v_cndmask_b32_e64 v84, v84, v85, s[44:45]
	v_cndmask_b32_e64 v86, v86, v87, s[46:47]
	s_waitcnt vmcnt(15)
; __global__ void __launch_bounds__(512, 2) mega(Params P0) {
;     ...
;             for (int ck = wv; ck < nchunk; ck += G * 8) { f32x4 v[16];
; #pragma unroll
;                 for (int j = 0; j < 16; ++j) v[j] = __builtin_nontemporal_load(h3 + (ck * 16 + j) * 64 + lane);
; #pragma unroll
;                 for (int j = 0; j < 16; ++j) { const int i = (ck * 16 + j) * 64 + lane; const int row = i >> 8, c4 = i & 255; const float rstd = rsqrtf(r3[row] * (1.0f / DM) + 1e-6f);
;                     __builtin_nontemporal_store(v[j] * rstd * *(const f32x4*)(fw + 4 * c4), (f32x4*)P.out + i); } } }
	v_pk_mul_f32 v[62:63], v[62:63], v[80:81] op_sel_hi:[1,0]
	v_pk_mul_f32 v[64:65], v[64:65], v[80:81] op_sel_hi:[1,0]
	v_pk_mul_f32 v[62:63], v[108:109], v[62:63]
	v_pk_mul_f32 v[64:65], v[110:111], v[64:65]
	s_waitcnt vmcnt(14)
	v_pk_mul_f32 v[58:59], v[58:59], v[80:81] op_sel_hi:[1,0]
	v_pk_mul_f32 v[60:61], v[60:61], v[80:81] op_sel_hi:[1,0]
	v_pk_mul_f32 v[58:59], v[112:113], v[58:59]
	v_pk_mul_f32 v[60:61], v[114:115], v[60:61]
	s_waitcnt vmcnt(13)
	v_pk_mul_f32 v[54:55], v[54:55], v[80:81] op_sel_hi:[1,0]
	v_pk_mul_f32 v[56:57], v[56:57], v[80:81] op_sel_hi:[1,0]
	v_pk_mul_f32 v[54:55], v[116:117], v[54:55]
	v_pk_mul_f32 v[56:57], v[118:119], v[56:57]
	s_waitcnt vmcnt(12)
	v_pk_mul_f32 v[50:51], v[50:51], v[80:81] op_sel_hi:[1,0]
	v_pk_mul_f32 v[52:53], v[52:53], v[80:81] op_sel_hi:[1,0]
	v_pk_mul_f32 v[50:51], v[120:121], v[50:51]
	v_pk_mul_f32 v[52:53], v[122:123], v[52:53]
	global_store_dwordx4 v[72:73], v[62:65], off nt
	global_store_dwordx4 v[72:73], v[58:61], off offset:1024 nt
	global_store_dwordx4 v[72:73], v[54:57], off offset:2048 nt
	global_store_dwordx4 v[72:73], v[50:53], off offset:3072 nt
	s_waitcnt vmcnt(15)
	v_pk_mul_f32 v[46:47], v[46:47], v[82:83] op_sel_hi:[1,0]
	v_pk_mul_f32 v[48:49], v[48:49], v[82:83] op_sel_hi:[1,0]
	v_pk_mul_f32 v[46:47], v[108:109], v[46:47]
	v_pk_mul_f32 v[48:49], v[110:111], v[48:49]
	s_waitcnt vmcnt(14)
	v_pk_mul_f32 v[42:43], v[42:43], v[82:83] op_sel_hi:[1,0]
	v_pk_mul_f32 v[44:45], v[44:45], v[82:83] op_sel_hi:[1,0]
	v_pk_mul_f32 v[42:43], v[112:113], v[42:43]
	v_pk_mul_f32 v[44:45], v[114:115], v[44:45]
	s_waitcnt vmcnt(13)
	v_pk_mul_f32 v[38:39], v[38:39], v[82:83] op_sel_hi:[1,0]
	v_pk_mul_f32 v[40:41], v[40:41], v[82:83] op_sel_hi:[1,0]
	v_pk_mul_f32 v[38:39], v[116:117], v[38:39]
	v_pk_mul_f32 v[40:41], v[118:119], v[40:41]
	s_waitcnt vmcnt(12)
	v_pk_mul_f32 v[34:35], v[34:35], v[82:83] op_sel_hi:[1,0]
	v_pk_mul_f32 v[36:37], v[36:37], v[82:83] op_sel_hi:[1,0]
	v_pk_mul_f32 v[34:35], v[120:121], v[34:35]
	v_pk_mul_f32 v[36:37], v[122:123], v[36:37]
	global_store_dwordx4 v[74:75], v[46:49], off nt
	global_store_dwordx4 v[74:75], v[42:45], off offset:1024 nt
	global_store_dwordx4 v[74:75], v[38:41], off offset:2048 nt
	global_store_dwordx4 v[74:75], v[34:37], off offset:3072 nt
	s_waitcnt vmcnt(15)
	v_pk_mul_f32 v[30:31], v[30:31], v[84:85] op_sel_hi:[1,0]
	v_pk_mul_f32 v[32:33], v[32:33], v[84:85] op_sel_hi:[1,0]
	v_pk_mul_f32 v[30:31], v[108:109], v[30:31]
	v_pk_mul_f32 v[32:33], v[110:111], v[32:33]
	s_waitcnt vmcnt(14)
	v_pk_mul_f32 v[26:27], v[26:27], v[84:85] op_sel_hi:[1,0]
	v_pk_mul_f32 v[28:29], v[28:29], v[84:85] op_sel_hi:[1,0]
	v_pk_mul_f32 v[26:27], v[112:113], v[26:27]
	v_pk_mul_f32 v[28:29], v[114:115], v[28:29]
	s_waitcnt vmcnt(13)
	v_pk_mul_f32 v[22:23], v[22:23], v[84:85] op_sel_hi:[1,0]
	v_pk_mul_f32 v[24:25], v[24:25], v[84:85] op_sel_hi:[1,0]
	v_pk_mul_f32 v[22:23], v[116:117], v[22:23]
	v_pk_mul_f32 v[24:25], v[118:119], v[24:25]
	s_waitcnt vmcnt(12)
	v_pk_mul_f32 v[18:19], v[18:19], v[84:85] op_sel_hi:[1,0]
	v_pk_mul_f32 v[20:21], v[20:21], v[84:85] op_sel_hi:[1,0]
	v_pk_mul_f32 v[18:19], v[120:121], v[18:19]
	v_pk_mul_f32 v[20:21], v[122:123], v[20:21]
	global_store_dwordx4 v[96:97], v[30:33], off nt
	global_store_dwordx4 v[96:97], v[26:29], off offset:1024 nt
	global_store_dwordx4 v[96:97], v[22:25], off offset:2048 nt
	global_store_dwordx4 v[96:97], v[18:21], off offset:3072 nt
	s_waitcnt vmcnt(15)
	v_pk_mul_f32 v[14:15], v[14:15], v[86:87] op_sel_hi:[1,0]
	v_pk_mul_f32 v[16:17], v[16:17], v[86:87] op_sel_hi:[1,0]
	v_pk_mul_f32 v[14:15], v[108:109], v[14:15]
	v_pk_mul_f32 v[16:17], v[110:111], v[16:17]
	s_waitcnt vmcnt(14)
	v_pk_mul_f32 v[10:11], v[10:11], v[86:87] op_sel_hi:[1,0]
	v_pk_mul_f32 v[12:13], v[12:13], v[86:87] op_sel_hi:[1,0]
	v_pk_mul_f32 v[10:11], v[112:113], v[10:11]
	v_pk_mul_f32 v[12:13], v[114:115], v[12:13]
	s_waitcnt vmcnt(13)
	v_pk_mul_f32 v[6:7], v[6:7], v[86:87] op_sel_hi:[1,0]
	v_pk_mul_f32 v[8:9], v[8:9], v[86:87] op_sel_hi:[1,0]
	v_pk_mul_f32 v[6:7], v[116:117], v[6:7]
	v_pk_mul_f32 v[8:9], v[118:119], v[8:9]
	s_waitcnt vmcnt(12)
	v_pk_mul_f32 v[2:3], v[2:3], v[86:87] op_sel_hi:[1,0]
	v_pk_mul_f32 v[4:5], v[4:5], v[86:87] op_sel_hi:[1,0]
	v_pk_mul_f32 v[2:3], v[120:121], v[2:3]
	v_pk_mul_f32 v[4:5], v[122:123], v[4:5]
	global_store_dwordx4 v[98:99], v[14:17], off nt
	global_store_dwordx4 v[98:99], v[10:13], off offset:1024 nt
	global_store_dwordx4 v[98:99], v[6:9], off offset:2048 nt
	global_store_dwordx4 v[98:99], v[2:5], off offset:3072 nt
	v_add_u32_e32 v70, s9, v70
	v_add_u32_e32 v101, s8, v101
	v_cmp_lt_i32_e32 vcc, s10, v100
	s_nop 1
	s_or_b64 s[6:7], vcc, s[6:7]
	s_andn2_b64 exec, exec, s[6:7]
	s_cbranch_execnz .LBB0_725
